# grid barrier spin loops poll without the sleep between loads
# baseline (speedup 1.0000x reference)
.LBB0_697:
	s_and_b32 s5, s4, 0xff
	s_mov_b64 s[36:37], -1
	s_cmp_lg_u32 s5, 0
	s_mov_b64 s[40:41], -1
	s_nop 0
	s_cbranch_scc1 .LBB0_700
	v_readlane_b32 s18, v254, 5
	v_readlane_b32 s19, v254, 6
	s_nop 4
	global_load_dword v0, v3, s[18:19] sc1
	s_waitcnt vmcnt(0)
	v_cmp_eq_u32_e32 vcc, 0, v0
	s_cbranch_vccnz .LBB0_702
	s_mov_b64 s[40:41], 0
	s_mov_b64 s[38:39], -1
